# best4 + nt on out-GEMM out stores
# baseline (speedup 1.0000x reference)
;     __device__ __forceinline__ void operator()(const f32x4 (&acc)[2][2][4][2], const Unit& u, int wr, int wc, int fr, int fq) const {
;     ...
;             const char* sp = (const char*)(stats + (size_t)u.pm * BM * 2);
;             unsigned soff0 = (unsigned)(wr * 64 + fr) * 8u, coff0 = (unsigned)(u.pn * BM + wc * 32 + 4 * fq) * 4u; asm volatile("" : "+v"(soff0), "+v"(coff0));
;             f32x4 gv[2][2], bv[2][2];
; #pragma unroll
;             for (int bj = 0; bj < 2; ++bj)
; #pragma unroll
;                 for (int n = 0; n < 2; ++n) { gv[bj][n] = *(const f32x4*)((const char*)lng + coff0 + (unsigned)(bj * HALF + n * 16) * 4u); bv[bj][n] = *(const f32x4*)((const char*)lnb + coff0 + (unsigned)(bj * HALF + n * 16) * 4u); }
; #pragma unroll
;             for (int ai = 0; ai < 2; ++ai)
; #pragma unroll
;                 for (int mh = 0; mh < 2; ++mh) {
;                     f32x4 bs[2][2][2]; f32x2_t st[2];
; #pragma unroll
;                     for (int mm = 0; mm < 2; ++mm) { st[mm] = *(const f32x2_t*)(sp + soff0 + (unsigned)(ai * HALF + (2 * mh + mm) * 16) * 8u);
; #pragma unroll
;                         for (int bj = 0; bj < 2; ++bj)
; #pragma unroll
;                             for (int n = 0; n < 2; ++n) bs[mm][bj][n] = *(const f32x4*)(bb + off0 + (unsigned)((ai * HALF + (2 * mh + mm) * 16) * 1024 + bj * HALF + n * 16) * 4u); }
; #pragma unroll
;                     for (int mm = 0; mm < 2; ++mm)
; #pragma unroll
;                         for (int bj = 0; bj < 2; ++bj)
; #pragma unroll
;                             for (int n = 0; n < 2; ++n) { const f32x4 hv = ((bs[mm][bj][n] - st[mm][0]) * st[mm][1]) * gv[bj][n] + bv[bj][n];
;                                 *(f32x4*)(ob + off0 + (unsigned)((ai * HALF + (2 * mh + mm) * 16) * 1024 + bj * HALF + n * 16) * 4u) = hv * DN_ALPHA + acc[ai][bj][2 * mh + mm][n]; }
;                     asm volatile("" : "+v"(off0), "+v"(soff0) :: "memory"); }
.LBB0_443:
	s_ashr_i32 s71, s70, 31
	s_lshl_b32 s86, s72, 8
	v_readlane_b32 s24, v253, 0
	s_lshl_b64 s[66:67], s[70:71], 18
	s_ashr_i32 s68, s86, 31
	v_readlane_b32 s25, v253, 1
	s_add_u32 s66, s66, s86
	s_load_dwordx4 s[76:79], s[24:25], 0xa8
	s_addc_u32 s67, s67, s68
	s_lshl_b64 s[66:67], s[66:67], 2
	s_add_u32 s68, s46, s66
	v_mov_b32_e32 v96, v212
	s_addc_u32 s69, s47, s67
	s_waitcnt lgkmcnt(0)
	s_add_u32 s66, s76, s66
	v_readfirstlane_b32 s73, v96
	s_addc_u32 s67, s77, s67
	s_ashr_i32 s72, s73, 2
	s_andn2_b32 s72, s72, 63
	v_and_or_b32 v130, v96, 15, s72
	s_lshr_b32 s72, s73, 1
	v_lshrrev_b32_e32 v96, 2, v96
	v_lshlrev_b32_e32 v132, 10, v130
	s_and_b32 s87, s72, 0x60
	v_and_b32_e32 v131, 12, v96
	v_or3_b32 v96, v132, s87, v131
	v_lshlrev_b32_e32 v96, 2, v96
	s_mov_b64 s[72:73], -1
	s_and_b64 vcc, exec, s[44:45]
	s_cbranch_vccz .LBB0_445
	s_or_b32 s72, s86, s87
	s_lshl_b64 s[70:71], s[70:71], 11
	v_lshlrev_b32_e32 v190, 3, v130
	v_or_b32_e32 v130, s72, v131
	v_readlane_b32 s24, v253, 37
	v_lshlrev_b32_e32 v134, 2, v130
	s_add_u32 s70, s24, s70
	v_readlane_b32 s24, v253, 38
	s_addc_u32 s71, s24, s71
	global_load_dwordx4 v[154:157], v134, s[54:55]
	global_load_dwordx4 v[158:161], v134, s[42:43]
	global_load_dwordx4 v[146:149], v134, s[54:55] offset:64
	global_load_dwordx4 v[150:153], v134, s[42:43] offset:64
	global_load_dwordx4 v[138:141], v134, s[54:55] offset:512
	global_load_dwordx4 v[142:145], v134, s[42:43] offset:512
	global_load_dwordx4 v[130:133], v134, s[54:55] offset:576
	s_nop 0
	global_load_dwordx4 v[134:137], v134, s[42:43] offset:576
	s_nop 0
	global_load_dwordx2 v[186:187], v190, s[70:71]
	global_load_dwordx4 v[202:205], v96, s[68:69]
	global_load_dwordx4 v[206:209], v96, s[68:69] offset:64
	global_load_dwordx4 v[230:233], v96, s[68:69] offset:512
	global_load_dwordx4 v[234:237], v96, s[68:69] offset:576
	global_load_dwordx2 v[182:183], v190, s[70:71] offset:128
	v_lshl_add_u64 v[162:163], s[68:69], 0, v[96:97]
	s_mov_b32 s24, 0x10000
	v_add_co_u32_e32 v162, vcc, s24, v162
	v_lshl_add_u64 v[184:185], s[66:67], 0, v[96:97]
	s_nop 0
	v_addc_co_u32_e32 v163, vcc, 0, v163, vcc
	global_load_dwordx4 v[238:241], v[162:163], off
	global_load_dwordx4 v[170:173], v[162:163], off offset:64
	global_load_dwordx4 v[166:169], v[162:163], off offset:512
	s_nop 0
	global_load_dwordx4 v[162:165], v[162:163], off offset:576
	v_add_co_u32_e32 v184, vcc, s24, v184
	s_mov_b32 s24, 0x20000
	s_nop 0
	v_addc_co_u32_e32 v185, vcc, 0, v185, vcc
	s_mov_b32 s25, 0x30000
	s_mov_b64 s[72:73], 0
	s_waitcnt vmcnt(0)
	v_sub_f32_e32 v193, v205, v186
	v_sub_f32_e32 v192, v204, v186
	v_sub_f32_e32 v203, v203, v186
	v_sub_f32_e32 v202, v202, v186
	v_pk_mul_f32 v[202:203], v[186:187], v[202:203] op_sel:[1,0]
	v_pk_mul_f32 v[192:193], v[186:187], v[192:193] op_sel:[1,0]
	v_pk_fma_f32 v[202:203], v[154:155], v[202:203], v[158:159]
	v_pk_fma_f32 v[192:193], v[156:157], v[192:193], v[160:161]
	v_pk_fma_f32 v[202:203], v[202:203], s[88:89], v[126:127] op_sel_hi:[1,0,1]
	v_pk_fma_f32 v[204:205], v[192:193], s[88:89], v[128:129] op_sel_hi:[1,0,1]
	global_store_dwordx4 v96, v[202:205], s[66:67] nt
	v_sub_f32_e32 v193, v209, v186
	v_sub_f32_e32 v192, v208, v186
	v_sub_f32_e32 v203, v207, v186
	v_sub_f32_e32 v202, v206, v186
	v_pk_mul_f32 v[202:203], v[186:187], v[202:203] op_sel:[1,0]
	v_pk_mul_f32 v[192:193], v[186:187], v[192:193] op_sel:[1,0]
	v_pk_fma_f32 v[202:203], v[146:147], v[202:203], v[150:151]
	v_pk_fma_f32 v[192:193], v[148:149], v[192:193], v[152:153]
	v_pk_fma_f32 v[202:203], v[202:203], s[88:89], v[122:123] op_sel_hi:[1,0,1]
	v_pk_fma_f32 v[204:205], v[192:193], s[88:89], v[124:125] op_sel_hi:[1,0,1]
	global_store_dwordx4 v96, v[202:205], s[66:67] offset:64 nt
	v_sub_f32_e32 v193, v233, v186
	v_sub_f32_e32 v192, v232, v186
	v_sub_f32_e32 v203, v231, v186
	v_sub_f32_e32 v202, v230, v186
	v_pk_mul_f32 v[202:203], v[186:187], v[202:203] op_sel:[1,0]
	v_pk_mul_f32 v[192:193], v[186:187], v[192:193] op_sel:[1,0]
	v_pk_fma_f32 v[202:203], v[138:139], v[202:203], v[142:143]
	v_pk_fma_f32 v[192:193], v[140:141], v[192:193], v[144:145]
	v_pk_fma_f32 v[202:203], v[202:203], s[88:89], v[118:119] op_sel_hi:[1,0,1]
	v_pk_fma_f32 v[204:205], v[192:193], s[88:89], v[120:121] op_sel_hi:[1,0,1]
	global_store_dwordx4 v96, v[202:205], s[66:67] offset:512 nt
	v_sub_f32_e32 v193, v237, v186
	v_sub_f32_e32 v192, v236, v186
	v_sub_f32_e32 v203, v235, v186
	v_sub_f32_e32 v202, v234, v186
	v_pk_mul_f32 v[202:203], v[186:187], v[202:203] op_sel:[1,0]
	v_pk_mul_f32 v[186:187], v[186:187], v[192:193] op_sel:[1,0]
	v_pk_fma_f32 v[192:193], v[130:131], v[202:203], v[134:135]
	v_pk_fma_f32 v[186:187], v[132:133], v[186:187], v[136:137]
	v_pk_fma_f32 v[202:203], v[192:193], s[88:89], v[114:115] op_sel_hi:[1,0,1]
	v_pk_fma_f32 v[204:205], v[186:187], s[88:89], v[116:117] op_sel_hi:[1,0,1]
	v_sub_f32_e32 v187, v239, v182
	v_sub_f32_e32 v186, v238, v182
	v_sub_f32_e32 v193, v241, v182
	v_sub_f32_e32 v192, v240, v182
	v_sub_f32_e32 v171, v171, v182
	v_sub_f32_e32 v170, v170, v182
	v_sub_f32_e32 v173, v173, v182
	v_sub_f32_e32 v172, v172, v182
	v_sub_f32_e32 v167, v167, v182
	v_sub_f32_e32 v166, v166, v182
	v_sub_f32_e32 v169, v169, v182
	v_sub_f32_e32 v168, v168, v182
	v_sub_f32_e32 v163, v163, v182
	v_sub_f32_e32 v162, v162, v182
	v_sub_f32_e32 v165, v165, v182
	v_sub_f32_e32 v164, v164, v182
	v_pk_mul_f32 v[192:193], v[182:183], v[192:193] op_sel:[1,0]
	v_pk_mul_f32 v[186:187], v[182:183], v[186:187] op_sel:[1,0]
	v_pk_mul_f32 v[172:173], v[182:183], v[172:173] op_sel:[1,0]
	v_pk_mul_f32 v[170:171], v[182:183], v[170:171] op_sel:[1,0]
	v_pk_mul_f32 v[168:169], v[182:183], v[168:169] op_sel:[1,0]
;     __device__ __forceinline__ void operator()(const f32x4 (&acc)[2][2][4][2], const Unit& u, int wr, int wc, int fr, int fq) const {
;     ...
;             for (int ai = 0; ai < 2; ++ai)
; #pragma unroll
;                 for (int mh = 0; mh < 2; ++mh) {
;                     f32x4 bs[2][2][2]; f32x2_t st[2];
; #pragma unroll
;                     for (int mm = 0; mm < 2; ++mm) { st[mm] = *(const f32x2_t*)(sp + soff0 + (unsigned)(ai * HALF + (2 * mh + mm) * 16) * 8u);
; #pragma unroll
;                         for (int bj = 0; bj < 2; ++bj)
; #pragma unroll
;                             for (int n = 0; n < 2; ++n) bs[mm][bj][n] = *(const f32x4*)(bb + off0 + (unsigned)((ai * HALF + (2 * mh + mm) * 16) * 1024 + bj * HALF + n * 16) * 4u); }
; #pragma unroll
;                     for (int mm = 0; mm < 2; ++mm)
; #pragma unroll
;                         for (int bj = 0; bj < 2; ++bj)
; #pragma unroll
;                             for (int n = 0; n < 2; ++n) { const f32x4 hv = ((bs[mm][bj][n] - st[mm][0]) * st[mm][1]) * gv[bj][n] + bv[bj][n];
;                                 *(f32x4*)(ob + off0 + (unsigned)((ai * HALF + (2 * mh + mm) * 16) * 1024 + bj * HALF + n * 16) * 4u) = hv * DN_ALPHA + acc[ai][bj][2 * mh + mm][n]; }
;                     asm volatile("" : "+v"(off0), "+v"(soff0) :: "memory"); }
	v_pk_mul_f32 v[166:167], v[182:183], v[166:167] op_sel:[1,0]
	v_pk_mul_f32 v[164:165], v[182:183], v[164:165] op_sel:[1,0]
	v_pk_mul_f32 v[162:163], v[182:183], v[162:163] op_sel:[1,0]
	v_pk_fma_f32 v[186:187], v[154:155], v[186:187], v[158:159]
	v_pk_fma_f32 v[192:193], v[156:157], v[192:193], v[160:161]
	v_pk_fma_f32 v[170:171], v[146:147], v[170:171], v[150:151]
	v_pk_fma_f32 v[172:173], v[148:149], v[172:173], v[152:153]
	v_pk_fma_f32 v[166:167], v[138:139], v[166:167], v[142:143]
	v_pk_fma_f32 v[168:169], v[140:141], v[168:169], v[144:145]
	v_pk_fma_f32 v[162:163], v[130:131], v[162:163], v[134:135]
	v_pk_fma_f32 v[164:165], v[132:133], v[164:165], v[136:137]
	global_store_dwordx4 v96, v[202:205], s[66:67] offset:576 nt
	v_pk_fma_f32 v[172:173], v[172:173], s[88:89], v[108:109] op_sel_hi:[1,0,1]
	v_pk_fma_f32 v[170:171], v[170:171], s[88:89], v[106:107] op_sel_hi:[1,0,1]
	v_pk_fma_f32 v[204:205], v[192:193], s[88:89], v[112:113] op_sel_hi:[1,0,1]
	v_pk_fma_f32 v[202:203], v[186:187], s[88:89], v[110:111] op_sel_hi:[1,0,1]
	v_pk_fma_f32 v[168:169], v[168:169], s[88:89], v[104:105] op_sel_hi:[1,0,1]
	v_pk_fma_f32 v[166:167], v[166:167], s[88:89], v[102:103] op_sel_hi:[1,0,1]
	v_pk_fma_f32 v[164:165], v[164:165], s[88:89], v[100:101] op_sel_hi:[1,0,1]
	v_pk_fma_f32 v[162:163], v[162:163], s[88:89], v[98:99] op_sel_hi:[1,0,1]
	global_store_dwordx4 v[184:185], v[202:205], off nt
	global_store_dwordx4 v[184:185], v[170:173], off offset:64 nt
	global_store_dwordx4 v[184:185], v[166:169], off offset:512 nt
	global_store_dwordx4 v[184:185], v[162:165], off offset:576 nt
	v_mov_b32_e32 v182, v96
	v_mov_b32_e32 v183, v97
	global_load_dwordx2 v[192:193], v190, s[70:71] offset:256
	v_lshl_add_u64 v[162:163], s[68:69], 0, v[182:183]
	v_add_co_u32_e32 v164, vcc, s24, v162
	v_lshl_add_u64 v[186:187], s[66:67], 0, v[182:183]
	s_nop 0
	v_addc_co_u32_e32 v165, vcc, 0, v163, vcc
	global_load_dwordx4 v[202:205], v[164:165], off
	global_load_dwordx4 v[206:209], v[164:165], off offset:64
	global_load_dwordx4 v[230:233], v[164:165], off offset:512
	global_load_dwordx4 v[234:237], v[164:165], off offset:576
	global_load_dwordx2 v[184:185], v190, s[70:71] offset:384
	v_add_co_u32_e32 v162, vcc, s25, v162
	s_waitcnt vmcnt(4)
	v_sub_f32_e32 v203, v203, v192
	v_addc_co_u32_e32 v163, vcc, 0, v163, vcc
	global_load_dwordx4 v[238:241], v[162:163], off
	global_load_dwordx4 v[170:173], v[162:163], off offset:64
	global_load_dwordx4 v[166:169], v[162:163], off offset:512
	s_nop 0
	global_load_dwordx4 v[162:165], v[162:163], off offset:576
	v_sub_f32_e32 v202, v202, v192
	v_sub_f32_e32 v205, v205, v192
	v_sub_f32_e32 v204, v204, v192
	v_pk_mul_f32 v[204:205], v[192:193], v[204:205] op_sel:[1,0]
	v_pk_mul_f32 v[202:203], v[192:193], v[202:203] op_sel:[1,0]
	v_pk_fma_f32 v[204:205], v[156:157], v[204:205], v[160:161]
	v_pk_fma_f32 v[202:203], v[154:155], v[202:203], v[158:159]
	v_add_co_u32_e32 v210, vcc, s24, v186
	v_pk_fma_f32 v[204:205], v[204:205], s[88:89], v[94:95] op_sel_hi:[1,0,1]
	v_pk_fma_f32 v[202:203], v[202:203], s[88:89], v[92:93] op_sel_hi:[1,0,1]
	v_addc_co_u32_e32 v211, vcc, 0, v187, vcc
	global_store_dwordx4 v[210:211], v[202:205], off nt
	v_add_co_u32_e32 v186, vcc, s25, v186
	s_waitcnt vmcnt(8)
	v_sub_f32_e32 v203, v207, v192
	v_sub_f32_e32 v202, v206, v192
	v_sub_f32_e32 v205, v209, v192
	v_sub_f32_e32 v204, v208, v192
	v_pk_mul_f32 v[204:205], v[192:193], v[204:205] op_sel:[1,0]
	v_pk_mul_f32 v[202:203], v[192:193], v[202:203] op_sel:[1,0]
	v_pk_fma_f32 v[204:205], v[148:149], v[204:205], v[152:153]
	v_pk_fma_f32 v[202:203], v[146:147], v[202:203], v[150:151]
	v_pk_fma_f32 v[204:205], v[204:205], s[88:89], v[90:91] op_sel_hi:[1,0,1]
	v_pk_fma_f32 v[202:203], v[202:203], s[88:89], v[88:89] op_sel_hi:[1,0,1]
	global_store_dwordx4 v[210:211], v[202:205], off offset:64 nt
	v_addc_co_u32_e32 v187, vcc, 0, v187, vcc
	s_waitcnt vmcnt(8)
	v_sub_f32_e32 v203, v231, v192
	v_sub_f32_e32 v202, v230, v192
	v_sub_f32_e32 v205, v233, v192
	v_sub_f32_e32 v204, v232, v192
	v_pk_mul_f32 v[204:205], v[192:193], v[204:205] op_sel:[1,0]
	v_pk_mul_f32 v[202:203], v[192:193], v[202:203] op_sel:[1,0]
	v_pk_fma_f32 v[204:205], v[140:141], v[204:205], v[144:145]
	v_pk_fma_f32 v[202:203], v[138:139], v[202:203], v[142:143]
	v_pk_fma_f32 v[204:205], v[204:205], s[88:89], v[86:87] op_sel_hi:[1,0,1]
	v_pk_fma_f32 v[202:203], v[202:203], s[88:89], v[84:85] op_sel_hi:[1,0,1]
	global_store_dwordx4 v[210:211], v[202:205], off offset:512 nt
	s_mov_b32 s24, 0x80000
	s_mov_b32 s25, 0x90000
	s_waitcnt vmcnt(8)
	v_sub_f32_e32 v203, v235, v192
	v_sub_f32_e32 v202, v234, v192
	v_sub_f32_e32 v205, v237, v192
	v_sub_f32_e32 v204, v236, v192
	v_pk_mul_f32 v[204:205], v[192:193], v[204:205] op_sel:[1,0]
	v_pk_mul_f32 v[192:193], v[192:193], v[202:203] op_sel:[1,0]
	v_pk_fma_f32 v[202:203], v[132:133], v[204:205], v[136:137]
	v_pk_fma_f32 v[192:193], v[130:131], v[192:193], v[134:135]
	v_pk_fma_f32 v[204:205], v[202:203], s[88:89], v[82:83] op_sel_hi:[1,0,1]
	v_pk_fma_f32 v[202:203], v[192:193], s[88:89], v[80:81] op_sel_hi:[1,0,1]
	global_store_dwordx4 v[210:211], v[202:205], off offset:576 nt
	s_waitcnt vmcnt(7)
	v_sub_f32_e32 v193, v239, v184
	v_sub_f32_e32 v192, v238, v184
	v_sub_f32_e32 v203, v241, v184
	v_sub_f32_e32 v202, v240, v184
	s_waitcnt vmcnt(6)
	v_sub_f32_e32 v171, v171, v184
	v_sub_f32_e32 v170, v170, v184
	v_sub_f32_e32 v173, v173, v184
	v_sub_f32_e32 v172, v172, v184
	s_waitcnt vmcnt(5)
	v_sub_f32_e32 v167, v167, v184
	v_sub_f32_e32 v166, v166, v184
	v_sub_f32_e32 v169, v169, v184
	v_sub_f32_e32 v168, v168, v184
	s_waitcnt vmcnt(4)
;     __device__ __forceinline__ void operator()(const f32x4 (&acc)[2][2][4][2], const Unit& u, int wr, int wc, int fr, int fq) const {
;     ...
;             for (int ai = 0; ai < 2; ++ai)
; #pragma unroll
;                 for (int mh = 0; mh < 2; ++mh) {
;                     f32x4 bs[2][2][2]; f32x2_t st[2];
; #pragma unroll
;                     for (int mm = 0; mm < 2; ++mm) { st[mm] = *(const f32x2_t*)(sp + soff0 + (unsigned)(ai * HALF + (2 * mh + mm) * 16) * 8u);
; #pragma unroll
;                         for (int bj = 0; bj < 2; ++bj)
; #pragma unroll
;                             for (int n = 0; n < 2; ++n) bs[mm][bj][n] = *(const f32x4*)(bb + off0 + (unsigned)((ai * HALF + (2 * mh + mm) * 16) * 1024 + bj * HALF + n * 16) * 4u); }
; #pragma unroll
;                     for (int mm = 0; mm < 2; ++mm)
; #pragma unroll
;                         for (int bj = 0; bj < 2; ++bj)
; #pragma unroll
;                             for (int n = 0; n < 2; ++n) { const f32x4 hv = ((bs[mm][bj][n] - st[mm][0]) * st[mm][1]) * gv[bj][n] + bv[bj][n];
;                                 *(f32x4*)(ob + off0 + (unsigned)((ai * HALF + (2 * mh + mm) * 16) * 1024 + bj * HALF + n * 16) * 4u) = hv * DN_ALPHA + acc[ai][bj][2 * mh + mm][n]; }
;                     asm volatile("" : "+v"(off0), "+v"(soff0) :: "memory"); }
	v_sub_f32_e32 v163, v163, v184
	v_sub_f32_e32 v162, v162, v184
	v_sub_f32_e32 v165, v165, v184
	v_sub_f32_e32 v164, v164, v184
	v_pk_mul_f32 v[202:203], v[184:185], v[202:203] op_sel:[1,0]
	v_pk_mul_f32 v[192:193], v[184:185], v[192:193] op_sel:[1,0]
	v_pk_mul_f32 v[172:173], v[184:185], v[172:173] op_sel:[1,0]
	v_pk_mul_f32 v[170:171], v[184:185], v[170:171] op_sel:[1,0]
	v_pk_mul_f32 v[168:169], v[184:185], v[168:169] op_sel:[1,0]
	v_pk_mul_f32 v[166:167], v[184:185], v[166:167] op_sel:[1,0]
	v_pk_mul_f32 v[164:165], v[184:185], v[164:165] op_sel:[1,0]
	v_pk_mul_f32 v[162:163], v[184:185], v[162:163] op_sel:[1,0]
	v_pk_fma_f32 v[192:193], v[154:155], v[192:193], v[158:159]
	v_pk_fma_f32 v[202:203], v[156:157], v[202:203], v[160:161]
	v_pk_fma_f32 v[170:171], v[146:147], v[170:171], v[150:151]
	v_pk_fma_f32 v[172:173], v[148:149], v[172:173], v[152:153]
	v_pk_fma_f32 v[166:167], v[138:139], v[166:167], v[142:143]
	v_pk_fma_f32 v[168:169], v[140:141], v[168:169], v[144:145]
	v_pk_fma_f32 v[162:163], v[130:131], v[162:163], v[134:135]
	v_pk_fma_f32 v[164:165], v[132:133], v[164:165], v[136:137]
	v_pk_fma_f32 v[204:205], v[202:203], s[88:89], v[78:79] op_sel_hi:[1,0,1]
	v_pk_fma_f32 v[202:203], v[192:193], s[88:89], v[76:77] op_sel_hi:[1,0,1]
	v_pk_fma_f32 v[172:173], v[172:173], s[88:89], v[74:75] op_sel_hi:[1,0,1]
	v_pk_fma_f32 v[170:171], v[170:171], s[88:89], v[72:73] op_sel_hi:[1,0,1]
	v_pk_fma_f32 v[168:169], v[168:169], s[88:89], v[70:71] op_sel_hi:[1,0,1]
	v_pk_fma_f32 v[166:167], v[166:167], s[88:89], v[68:69] op_sel_hi:[1,0,1]
	v_pk_fma_f32 v[164:165], v[164:165], s[88:89], v[66:67] op_sel_hi:[1,0,1]
	v_pk_fma_f32 v[162:163], v[162:163], s[88:89], v[64:65] op_sel_hi:[1,0,1]
	global_store_dwordx4 v[186:187], v[202:205], off nt
	global_store_dwordx4 v[186:187], v[170:173], off offset:64 nt
	global_store_dwordx4 v[186:187], v[166:169], off offset:512 nt
	global_store_dwordx4 v[186:187], v[162:165], off offset:576 nt
	global_load_dwordx2 v[210:211], v190, s[70:71] offset:1024
	v_lshl_add_u64 v[192:193], s[68:69], 0, v[182:183]
	v_add_co_u32_e32 v184, vcc, s24, v192
	s_nop 1
	v_addc_co_u32_e32 v185, vcc, 0, v193, vcc
	global_load_dwordx4 v[162:165], v[184:185], off
	global_load_dwordx4 v[166:169], v[184:185], off offset:64
	global_load_dwordx4 v[170:173], v[184:185], off offset:512
	s_nop 0
	global_load_dwordx4 v[184:187], v[184:185], off offset:576
	s_nop 0
	global_load_dwordx2 v[238:239], v190, s[70:71] offset:1152
	v_add_co_u32_e32 v192, vcc, s25, v192
	s_waitcnt vmcnt(4)
	v_sub_f32_e32 v163, v163, v210
	v_addc_co_u32_e32 v193, vcc, 0, v193, vcc
	global_load_dwordx4 v[202:205], v[192:193], off
	global_load_dwordx4 v[206:209], v[192:193], off offset:64
	global_load_dwordx4 v[230:233], v[192:193], off offset:512
	global_load_dwordx4 v[234:237], v[192:193], off offset:576
	v_sub_f32_e32 v162, v162, v210
	v_sub_f32_e32 v165, v165, v210
	v_sub_f32_e32 v164, v164, v210
	v_lshl_add_u64 v[192:193], s[66:67], 0, v[182:183]
	v_pk_mul_f32 v[164:165], v[210:211], v[164:165] op_sel:[1,0]
	v_pk_mul_f32 v[162:163], v[210:211], v[162:163] op_sel:[1,0]
	v_pk_fma_f32 v[164:165], v[156:157], v[164:165], v[160:161]
	v_pk_fma_f32 v[162:163], v[154:155], v[162:163], v[158:159]
	v_add_co_u32_e32 v240, vcc, s24, v192
	v_pk_fma_f32 v[164:165], v[164:165], s[88:89], v[62:63] op_sel_hi:[1,0,1]
	v_pk_fma_f32 v[162:163], v[162:163], s[88:89], v[60:61] op_sel_hi:[1,0,1]
	v_addc_co_u32_e32 v241, vcc, 0, v193, vcc
	global_store_dwordx4 v[240:241], v[162:165], off nt
	s_mov_b32 s24, 0xa0000
	s_waitcnt vmcnt(8)
	v_sub_f32_e32 v163, v167, v210
	v_sub_f32_e32 v162, v166, v210
	v_sub_f32_e32 v165, v169, v210
	v_sub_f32_e32 v164, v168, v210
	v_pk_mul_f32 v[164:165], v[210:211], v[164:165] op_sel:[1,0]
	v_pk_mul_f32 v[162:163], v[210:211], v[162:163] op_sel:[1,0]
	v_pk_fma_f32 v[164:165], v[148:149], v[164:165], v[152:153]
	v_pk_fma_f32 v[162:163], v[146:147], v[162:163], v[150:151]
	v_pk_fma_f32 v[164:165], v[164:165], s[88:89], v[58:59] op_sel_hi:[1,0,1]
	v_pk_fma_f32 v[162:163], v[162:163], s[88:89], v[56:57] op_sel_hi:[1,0,1]
	global_store_dwordx4 v[240:241], v[162:165], off offset:64 nt
	v_add_co_u32_e32 v166, vcc, s25, v192
	s_waitcnt vmcnt(8)
	v_sub_f32_e32 v163, v171, v210
	v_sub_f32_e32 v162, v170, v210
	v_sub_f32_e32 v165, v173, v210
	v_sub_f32_e32 v164, v172, v210
	v_pk_mul_f32 v[164:165], v[210:211], v[164:165] op_sel:[1,0]
	v_pk_mul_f32 v[162:163], v[210:211], v[162:163] op_sel:[1,0]
	v_pk_fma_f32 v[164:165], v[140:141], v[164:165], v[144:145]
	v_pk_fma_f32 v[162:163], v[138:139], v[162:163], v[142:143]
	v_pk_fma_f32 v[164:165], v[164:165], s[88:89], v[54:55] op_sel_hi:[1,0,1]
	v_pk_fma_f32 v[162:163], v[162:163], s[88:89], v[52:53] op_sel_hi:[1,0,1]
	global_store_dwordx4 v[240:241], v[162:165], off offset:512 nt
	v_addc_co_u32_e32 v167, vcc, 0, v193, vcc
	s_waitcnt vmcnt(8)
	v_sub_f32_e32 v163, v185, v210
	v_sub_f32_e32 v162, v184, v210
	v_sub_f32_e32 v165, v187, v210
	v_sub_f32_e32 v164, v186, v210
	v_pk_mul_f32 v[164:165], v[210:211], v[164:165] op_sel:[1,0]
	v_pk_mul_f32 v[162:163], v[210:211], v[162:163] op_sel:[1,0]
	v_pk_fma_f32 v[164:165], v[132:133], v[164:165], v[136:137]
	v_pk_fma_f32 v[162:163], v[130:131], v[162:163], v[134:135]
	v_pk_fma_f32 v[164:165], v[164:165], s[88:89], v[50:51] op_sel_hi:[1,0,1]
	v_pk_fma_f32 v[162:163], v[162:163], s[88:89], v[48:49] op_sel_hi:[1,0,1]
	global_store_dwordx4 v[240:241], v[162:165], off offset:576 nt
	s_mov_b32 s25, 0xb0000
	s_waitcnt vmcnt(7)
;     __device__ __forceinline__ void operator()(const f32x4 (&acc)[2][2][4][2], const Unit& u, int wr, int wc, int fr, int fq) const {
;     ...
;             for (int ai = 0; ai < 2; ++ai)
; #pragma unroll
;                 for (int mh = 0; mh < 2; ++mh) {
;                     f32x4 bs[2][2][2]; f32x2_t st[2];
; #pragma unroll
;                     for (int mm = 0; mm < 2; ++mm) { st[mm] = *(const f32x2_t*)(sp + soff0 + (unsigned)(ai * HALF + (2 * mh + mm) * 16) * 8u);
; #pragma unroll
;                         for (int bj = 0; bj < 2; ++bj)
; #pragma unroll
;                             for (int n = 0; n < 2; ++n) bs[mm][bj][n] = *(const f32x4*)(bb + off0 + (unsigned)((ai * HALF + (2 * mh + mm) * 16) * 1024 + bj * HALF + n * 16) * 4u); }
; #pragma unroll
;                     for (int mm = 0; mm < 2; ++mm)
; #pragma unroll
;                         for (int bj = 0; bj < 2; ++bj)
; #pragma unroll
;                             for (int n = 0; n < 2; ++n) { const f32x4 hv = ((bs[mm][bj][n] - st[mm][0]) * st[mm][1]) * gv[bj][n] + bv[bj][n];
;                                 *(f32x4*)(ob + off0 + (unsigned)((ai * HALF + (2 * mh + mm) * 16) * 1024 + bj * HALF + n * 16) * 4u) = hv * DN_ALPHA + acc[ai][bj][2 * mh + mm][n]; }
;                     asm volatile("" : "+v"(off0), "+v"(soff0) :: "memory"); }
	v_sub_f32_e32 v163, v203, v238
	v_sub_f32_e32 v162, v202, v238
	v_sub_f32_e32 v165, v205, v238
	v_sub_f32_e32 v164, v204, v238
	v_pk_mul_f32 v[164:165], v[238:239], v[164:165] op_sel:[1,0]
	v_pk_mul_f32 v[162:163], v[238:239], v[162:163] op_sel:[1,0]
	v_pk_fma_f32 v[164:165], v[156:157], v[164:165], v[160:161]
	v_pk_fma_f32 v[162:163], v[154:155], v[162:163], v[158:159]
	v_pk_fma_f32 v[164:165], v[164:165], s[88:89], v[46:47] op_sel_hi:[1,0,1]
	v_pk_fma_f32 v[162:163], v[162:163], s[88:89], v[44:45] op_sel_hi:[1,0,1]
	global_store_dwordx4 v[166:167], v[162:165], off nt
	s_waitcnt vmcnt(7)
	s_nop 0
	v_sub_f32_e32 v163, v207, v238
	v_sub_f32_e32 v162, v206, v238
	v_sub_f32_e32 v165, v209, v238
	v_sub_f32_e32 v164, v208, v238
	v_pk_mul_f32 v[164:165], v[238:239], v[164:165] op_sel:[1,0]
	v_pk_mul_f32 v[162:163], v[238:239], v[162:163] op_sel:[1,0]
	v_pk_fma_f32 v[164:165], v[148:149], v[164:165], v[152:153]
	v_pk_fma_f32 v[162:163], v[146:147], v[162:163], v[150:151]
	v_pk_fma_f32 v[164:165], v[164:165], s[88:89], v[42:43] op_sel_hi:[1,0,1]
	v_pk_fma_f32 v[162:163], v[162:163], s[88:89], v[40:41] op_sel_hi:[1,0,1]
	global_store_dwordx4 v[166:167], v[162:165], off offset:64 nt
	s_waitcnt vmcnt(7)
	s_nop 0
	v_sub_f32_e32 v163, v231, v238
	v_sub_f32_e32 v162, v230, v238
	v_sub_f32_e32 v165, v233, v238
	v_sub_f32_e32 v164, v232, v238
	v_pk_mul_f32 v[164:165], v[238:239], v[164:165] op_sel:[1,0]
	v_pk_mul_f32 v[162:163], v[238:239], v[162:163] op_sel:[1,0]
	v_pk_fma_f32 v[164:165], v[140:141], v[164:165], v[144:145]
	v_pk_fma_f32 v[162:163], v[138:139], v[162:163], v[142:143]
	v_pk_fma_f32 v[164:165], v[164:165], s[88:89], v[38:39] op_sel_hi:[1,0,1]
	v_pk_fma_f32 v[162:163], v[162:163], s[88:89], v[36:37] op_sel_hi:[1,0,1]
	global_store_dwordx4 v[166:167], v[162:165], off offset:512 nt
	s_waitcnt vmcnt(7)
	s_nop 0
	v_sub_f32_e32 v163, v235, v238
	v_sub_f32_e32 v162, v234, v238
	v_sub_f32_e32 v165, v237, v238
	v_sub_f32_e32 v164, v236, v238
	v_pk_mul_f32 v[164:165], v[238:239], v[164:165] op_sel:[1,0]
	v_pk_mul_f32 v[162:163], v[238:239], v[162:163] op_sel:[1,0]
	v_pk_fma_f32 v[164:165], v[132:133], v[164:165], v[136:137]
	v_pk_fma_f32 v[162:163], v[130:131], v[162:163], v[134:135]
	v_pk_fma_f32 v[164:165], v[164:165], s[88:89], v[30:31] op_sel_hi:[1,0,1]
	v_pk_fma_f32 v[162:163], v[162:163], s[88:89], v[28:29] op_sel_hi:[1,0,1]
	global_store_dwordx4 v[166:167], v[162:165], off offset:576 nt
	global_load_dwordx2 v[210:211], v190, s[70:71] offset:1280
	v_lshl_add_u64 v[192:193], s[68:69], 0, v[182:183]
	v_add_co_u32_e32 v184, vcc, s24, v192
	s_nop 1
	v_addc_co_u32_e32 v185, vcc, 0, v193, vcc
	global_load_dwordx4 v[162:165], v[184:185], off
	global_load_dwordx4 v[166:169], v[184:185], off offset:64
	global_load_dwordx4 v[170:173], v[184:185], off offset:512
	s_nop 0
	global_load_dwordx4 v[184:187], v[184:185], off offset:576
	s_nop 0
	global_load_dwordx2 v[238:239], v190, s[70:71] offset:1408
	v_add_co_u32_e32 v192, vcc, s25, v192
	s_waitcnt vmcnt(4)
	v_sub_f32_e32 v163, v163, v210
	v_addc_co_u32_e32 v193, vcc, 0, v193, vcc
	global_load_dwordx4 v[202:205], v[192:193], off
	global_load_dwordx4 v[206:209], v[192:193], off offset:64
	global_load_dwordx4 v[230:233], v[192:193], off offset:512
	global_load_dwordx4 v[234:237], v[192:193], off offset:576
	v_sub_f32_e32 v162, v162, v210
	v_sub_f32_e32 v165, v165, v210
	v_sub_f32_e32 v164, v164, v210
	v_lshl_add_u64 v[192:193], s[66:67], 0, v[182:183]
	v_pk_mul_f32 v[164:165], v[210:211], v[164:165] op_sel:[1,0]
	v_pk_mul_f32 v[162:163], v[210:211], v[162:163] op_sel:[1,0]
	v_pk_fma_f32 v[164:165], v[156:157], v[164:165], v[160:161]
	v_pk_fma_f32 v[162:163], v[154:155], v[162:163], v[158:159]
	v_add_co_u32_e32 v240, vcc, s24, v192
	v_pk_fma_f32 v[164:165], v[164:165], s[88:89], v[34:35] op_sel_hi:[1,0,1]
	v_pk_fma_f32 v[162:163], v[162:163], s[88:89], v[32:33] op_sel_hi:[1,0,1]
	v_addc_co_u32_e32 v241, vcc, 0, v193, vcc
	global_store_dwordx4 v[240:241], v[162:165], off nt
	s_waitcnt vmcnt(8)
	s_nop 0
	v_sub_f32_e32 v163, v167, v210
	v_sub_f32_e32 v162, v166, v210
	v_sub_f32_e32 v165, v169, v210
	v_sub_f32_e32 v164, v168, v210
	v_pk_mul_f32 v[164:165], v[210:211], v[164:165] op_sel:[1,0]
	v_pk_mul_f32 v[162:163], v[210:211], v[162:163] op_sel:[1,0]
	v_pk_fma_f32 v[164:165], v[148:149], v[164:165], v[152:153]
	v_pk_fma_f32 v[162:163], v[146:147], v[162:163], v[150:151]
	v_pk_fma_f32 v[164:165], v[164:165], s[88:89], v[26:27] op_sel_hi:[1,0,1]
	v_pk_fma_f32 v[162:163], v[162:163], s[88:89], v[24:25] op_sel_hi:[1,0,1]
	global_store_dwordx4 v[240:241], v[162:165], off offset:64 nt
	s_waitcnt vmcnt(8)
	s_nop 0
	v_sub_f32_e32 v163, v171, v210
	v_sub_f32_e32 v162, v170, v210
	v_sub_f32_e32 v165, v173, v210
	v_sub_f32_e32 v164, v172, v210
	v_pk_mul_f32 v[164:165], v[210:211], v[164:165] op_sel:[1,0]
	v_pk_mul_f32 v[162:163], v[210:211], v[162:163] op_sel:[1,0]
	v_pk_fma_f32 v[164:165], v[140:141], v[164:165], v[144:145]
	v_pk_fma_f32 v[162:163], v[138:139], v[162:163], v[142:143]
	v_pk_fma_f32 v[164:165], v[164:165], s[88:89], v[22:23] op_sel_hi:[1,0,1]
	v_pk_fma_f32 v[162:163], v[162:163], s[88:89], v[20:21] op_sel_hi:[1,0,1]
	global_store_dwordx4 v[240:241], v[162:165], off offset:512 nt
	s_waitcnt vmcnt(8)
	s_nop 0
	v_sub_f32_e32 v163, v185, v210
	v_sub_f32_e32 v162, v184, v210
	v_sub_f32_e32 v165, v187, v210
	v_sub_f32_e32 v164, v186, v210
	v_pk_mul_f32 v[164:165], v[210:211], v[164:165] op_sel:[1,0]
	v_pk_mul_f32 v[162:163], v[210:211], v[162:163] op_sel:[1,0]
	v_pk_fma_f32 v[164:165], v[132:133], v[164:165], v[136:137]
	v_pk_fma_f32 v[162:163], v[130:131], v[162:163], v[134:135]
	v_pk_fma_f32 v[164:165], v[164:165], s[88:89], v[18:19] op_sel_hi:[1,0,1]
	v_pk_fma_f32 v[162:163], v[162:163], s[88:89], v[16:17] op_sel_hi:[1,0,1]
	global_store_dwordx4 v[240:241], v[162:165], off offset:576 nt
	s_waitcnt vmcnt(7)
;     __device__ __forceinline__ void operator()(const f32x4 (&acc)[2][2][4][2], const Unit& u, int wr, int wc, int fr, int fq) const {
;     ...
;         if (stats == nullptr) {
; #pragma unroll
;             for (int ai = 0; ai < 2; ++ai) {
;                 f32x4 bs[4][2][2];
; #pragma unroll
;                 for (int m = 0; m < 4; ++m)
; #pragma unroll
;                     for (int bj = 0; bj < 2; ++bj)
; #pragma unroll
;                         for (int n = 0; n < 2; ++n) bs[m][bj][n] = *(const f32x4*)(bb + off0 + (unsigned)((ai * HALF + m * 16) * 1024 + bj * HALF + n * 16) * 4u);
; #pragma unroll
;                 for (int m = 0; m < 4; ++m)
; #pragma unroll
;                     for (int bj = 0; bj < 2; ++bj)
; #pragma unroll
;                         for (int n = 0; n < 2; ++n) *(f32x4*)(ob + off0 + (unsigned)((ai * HALF + m * 16) * 1024 + bj * HALF + n * 16) * 4u) = bs[m][bj][n] * DN_ALPHA + acc[ai][bj][m][n];
;                 asm volatile("" : "+v"(off0) :: "memory"); }
;     ...
;                             for (int n = 0; n < 2; ++n) { const f32x4 hv = ((bs[mm][bj][n] - st[mm][0]) * st[mm][1]) * gv[bj][n] + bv[bj][n];
;                                 *(f32x4*)(ob + off0 + (unsigned)((ai * HALF + (2 * mh + mm) * 16) * 1024 + bj * HALF + n * 16) * 4u) = hv * DN_ALPHA + acc[ai][bj][2 * mh + mm][n]; }
	s_nop 0
	v_sub_f32_e32 v163, v203, v238
	v_sub_f32_e32 v162, v202, v238
	v_sub_f32_e32 v165, v205, v238
	v_sub_f32_e32 v164, v204, v238
	v_pk_mul_f32 v[164:165], v[238:239], v[164:165] op_sel:[1,0]
	v_pk_mul_f32 v[162:163], v[238:239], v[162:163] op_sel:[1,0]
	v_pk_fma_f32 v[156:157], v[156:157], v[164:165], v[160:161]
	v_pk_fma_f32 v[154:155], v[154:155], v[162:163], v[158:159]
	v_add_co_u32_e32 v158, vcc, s25, v192
	v_pk_fma_f32 v[156:157], v[156:157], s[88:89], v[14:15] op_sel_hi:[1,0,1]
	v_pk_fma_f32 v[154:155], v[154:155], s[88:89], v[12:13] op_sel_hi:[1,0,1]
	v_addc_co_u32_e32 v159, vcc, 0, v193, vcc
	global_store_dwordx4 v[158:159], v[154:157], off nt
	s_waitcnt vmcnt(7)
	s_nop 0
	v_sub_f32_e32 v155, v207, v238
	v_sub_f32_e32 v154, v206, v238
	v_sub_f32_e32 v157, v209, v238
	v_sub_f32_e32 v156, v208, v238
	v_pk_mul_f32 v[156:157], v[238:239], v[156:157] op_sel:[1,0]
	v_pk_mul_f32 v[154:155], v[238:239], v[154:155] op_sel:[1,0]
	v_pk_fma_f32 v[148:149], v[148:149], v[156:157], v[152:153]
	v_pk_fma_f32 v[146:147], v[146:147], v[154:155], v[150:151]
	v_pk_fma_f32 v[148:149], v[148:149], s[88:89], v[10:11] op_sel_hi:[1,0,1]
	v_pk_fma_f32 v[146:147], v[146:147], s[88:89], v[8:9] op_sel_hi:[1,0,1]
	global_store_dwordx4 v[158:159], v[146:149], off offset:64 nt
	s_waitcnt vmcnt(7)
	s_nop 0
	v_sub_f32_e32 v147, v231, v238
	v_sub_f32_e32 v146, v230, v238
	v_sub_f32_e32 v149, v233, v238
	v_sub_f32_e32 v148, v232, v238
	v_pk_mul_f32 v[148:149], v[238:239], v[148:149] op_sel:[1,0]
	v_pk_mul_f32 v[146:147], v[238:239], v[146:147] op_sel:[1,0]
	v_pk_fma_f32 v[140:141], v[140:141], v[148:149], v[144:145]
	v_pk_fma_f32 v[138:139], v[138:139], v[146:147], v[142:143]
	v_pk_fma_f32 v[140:141], v[140:141], s[88:89], v[6:7] op_sel_hi:[1,0,1]
	v_pk_fma_f32 v[138:139], v[138:139], s[88:89], v[4:5] op_sel_hi:[1,0,1]
	global_store_dwordx4 v[158:159], v[138:141], off offset:512 nt
	s_waitcnt vmcnt(7)
	s_nop 0
	v_sub_f32_e32 v139, v235, v238
	v_sub_f32_e32 v138, v234, v238
	v_sub_f32_e32 v141, v237, v238
	v_sub_f32_e32 v140, v236, v238
	v_pk_mul_f32 v[140:141], v[238:239], v[140:141] op_sel:[1,0]
	v_pk_mul_f32 v[138:139], v[238:239], v[138:139] op_sel:[1,0]
	v_pk_fma_f32 v[132:133], v[132:133], v[140:141], v[136:137]
	v_pk_fma_f32 v[130:131], v[130:131], v[138:139], v[134:135]
	v_pk_fma_f32 v[132:133], v[132:133], s[88:89], v[2:3] op_sel_hi:[1,0,1]
	v_pk_fma_f32 v[130:131], v[130:131], s[88:89], v[0:1] op_sel_hi:[1,0,1]
	global_store_dwordx4 v[158:159], v[130:133], off offset:576 nt
.LBB0_445:
	s_andn2_b64 vcc, exec, s[72:73]
	v_readlane_b32 s78, v252, 44
	v_readlane_b32 s79, v252, 45
	s_cbranch_vccnz .LBB0_447
	v_lshl_add_u64 v[130:131], s[68:69], 0, v[96:97]
	global_load_dwordx4 v[144:147], v96, s[68:69]
	global_load_dwordx4 v[148:151], v96, s[68:69] offset:64
	global_load_dwordx4 v[152:155], v96, s[68:69] offset:512
	global_load_dwordx4 v[156:159], v96, s[68:69] offset:576
	v_add_co_u32_e32 v132, vcc, 0x10000, v130
	v_lshl_add_u64 v[142:143], s[66:67], 0, v[96:97]
	s_nop 0
	v_addc_co_u32_e32 v133, vcc, 0, v131, vcc
	global_load_dwordx4 v[160:163], v[132:133], off
	global_load_dwordx4 v[164:167], v[132:133], off offset:64
	global_load_dwordx4 v[168:171], v[132:133], off offset:512
	global_load_dwordx4 v[182:185], v[132:133], off offset:576
	v_add_co_u32_e32 v132, vcc, 0x20000, v130
	s_mov_b32 s24, 0x10000
	s_nop 0
	v_addc_co_u32_e32 v133, vcc, 0, v131, vcc
	global_load_dwordx4 v[190:193], v[132:133], off
	global_load_dwordx4 v[202:205], v[132:133], off offset:64
	global_load_dwordx4 v[206:209], v[132:133], off offset:512
	global_load_dwordx4 v[230:233], v[132:133], off offset:576
	v_add_co_u32_e32 v130, vcc, 0x30000, v130
	s_mov_b32 s25, 0x90000
	s_nop 0
	v_addc_co_u32_e32 v131, vcc, 0, v131, vcc
	global_load_dwordx4 v[234:237], v[130:131], off
	global_load_dwordx4 v[138:141], v[130:131], off offset:64
	global_load_dwordx4 v[134:137], v[130:131], off offset:512
	s_nop 0
	global_load_dwordx4 v[130:133], v[130:131], off offset:576
	s_waitcnt vmcnt(0)
	v_pk_fma_f32 v[126:127], v[144:145], s[88:89], v[126:127] op_sel_hi:[1,0,1]
	v_pk_fma_f32 v[128:129], v[146:147], s[88:89], v[128:129] op_sel_hi:[1,0,1]
	v_pk_fma_f32 v[122:123], v[148:149], s[88:89], v[122:123] op_sel_hi:[1,0,1]
	v_pk_fma_f32 v[114:115], v[156:157], s[88:89], v[114:115] op_sel_hi:[1,0,1]
	v_pk_fma_f32 v[116:117], v[158:159], s[88:89], v[116:117] op_sel_hi:[1,0,1]
	global_store_dwordx4 v96, v[114:117], s[66:67] offset:576 nt
	v_pk_fma_f32 v[124:125], v[150:151], s[88:89], v[124:125] op_sel_hi:[1,0,1]
	v_pk_fma_f32 v[118:119], v[152:153], s[88:89], v[118:119] op_sel_hi:[1,0,1]
	v_add_co_u32_e32 v114, vcc, s24, v142
	v_pk_fma_f32 v[100:101], v[184:185], s[88:89], v[100:101] op_sel_hi:[1,0,1]
	s_nop 0
	v_addc_co_u32_e32 v115, vcc, 0, v143, vcc
	v_pk_fma_f32 v[98:99], v[182:183], s[88:89], v[98:99] op_sel_hi:[1,0,1]
	s_mov_b32 s24, 0x20000
	global_store_dwordx4 v[114:115], v[98:101], off offset:576 nt
	v_pk_fma_f32 v[82:83], v[232:233], s[88:89], v[82:83] op_sel_hi:[1,0,1]
	v_pk_fma_f32 v[80:81], v[230:231], s[88:89], v[80:81] op_sel_hi:[1,0,1]
	v_add_co_u32_e32 v98, vcc, s24, v142
	s_mov_b32 s24, 0x30000
	s_nop 0
	v_addc_co_u32_e32 v99, vcc, 0, v143, vcc
	global_store_dwordx4 v[98:99], v[80:83], off offset:576 nt
	v_pk_fma_f32 v[120:121], v[154:155], s[88:89], v[120:121] op_sel_hi:[1,0,1]
	v_pk_fma_f32 v[112:113], v[162:163], s[88:89], v[112:113] op_sel_hi:[1,0,1]
	v_add_co_u32_e32 v80, vcc, s24, v142
	v_pk_fma_f32 v[110:111], v[160:161], s[88:89], v[110:111] op_sel_hi:[1,0,1]
	v_pk_fma_f32 v[108:109], v[166:167], s[88:89], v[108:109] op_sel_hi:[1,0,1]
	v_pk_fma_f32 v[106:107], v[164:165], s[88:89], v[106:107] op_sel_hi:[1,0,1]
;     __device__ __forceinline__ void operator()(const f32x4 (&acc)[2][2][4][2], const Unit& u, int wr, int wc, int fr, int fq) const {
;     ...
;         if (stats == nullptr) {
; #pragma unroll
;             for (int ai = 0; ai < 2; ++ai) {
;                 f32x4 bs[4][2][2];
; #pragma unroll
;                 for (int m = 0; m < 4; ++m)
; #pragma unroll
;                     for (int bj = 0; bj < 2; ++bj)
; #pragma unroll
;                         for (int n = 0; n < 2; ++n) bs[m][bj][n] = *(const f32x4*)(bb + off0 + (unsigned)((ai * HALF + m * 16) * 1024 + bj * HALF + n * 16) * 4u);
; #pragma unroll
;                 for (int m = 0; m < 4; ++m)
; #pragma unroll
;                     for (int bj = 0; bj < 2; ++bj)
; #pragma unroll
;                         for (int n = 0; n < 2; ++n) *(f32x4*)(ob + off0 + (unsigned)((ai * HALF + m * 16) * 1024 + bj * HALF + n * 16) * 4u) = bs[m][bj][n] * DN_ALPHA + acc[ai][bj][m][n];
;                 asm volatile("" : "+v"(off0) :: "memory"); }
	v_pk_fma_f32 v[104:105], v[170:171], s[88:89], v[104:105] op_sel_hi:[1,0,1]
	v_pk_fma_f32 v[102:103], v[168:169], s[88:89], v[102:103] op_sel_hi:[1,0,1]
	v_pk_fma_f32 v[94:95], v[192:193], s[88:89], v[94:95] op_sel_hi:[1,0,1]
	v_pk_fma_f32 v[92:93], v[190:191], s[88:89], v[92:93] op_sel_hi:[1,0,1]
	v_pk_fma_f32 v[90:91], v[204:205], s[88:89], v[90:91] op_sel_hi:[1,0,1]
	v_pk_fma_f32 v[88:89], v[202:203], s[88:89], v[88:89] op_sel_hi:[1,0,1]
	v_pk_fma_f32 v[86:87], v[208:209], s[88:89], v[86:87] op_sel_hi:[1,0,1]
	v_pk_fma_f32 v[84:85], v[206:207], s[88:89], v[84:85] op_sel_hi:[1,0,1]
	v_pk_fma_f32 v[78:79], v[236:237], s[88:89], v[78:79] op_sel_hi:[1,0,1]
	v_pk_fma_f32 v[76:77], v[234:235], s[88:89], v[76:77] op_sel_hi:[1,0,1]
	v_addc_co_u32_e32 v81, vcc, 0, v143, vcc
	v_pk_fma_f32 v[74:75], v[140:141], s[88:89], v[74:75] op_sel_hi:[1,0,1]
	v_pk_fma_f32 v[72:73], v[138:139], s[88:89], v[72:73] op_sel_hi:[1,0,1]
	v_pk_fma_f32 v[70:71], v[136:137], s[88:89], v[70:71] op_sel_hi:[1,0,1]
	v_pk_fma_f32 v[68:69], v[134:135], s[88:89], v[68:69] op_sel_hi:[1,0,1]
	v_pk_fma_f32 v[66:67], v[132:133], s[88:89], v[66:67] op_sel_hi:[1,0,1]
	v_pk_fma_f32 v[64:65], v[130:131], s[88:89], v[64:65] op_sel_hi:[1,0,1]
	global_store_dwordx4 v96, v[126:129], s[66:67] nt
	global_store_dwordx4 v96, v[122:125], s[66:67] offset:64 nt
	global_store_dwordx4 v96, v[118:121], s[66:67] offset:512 nt
	global_store_dwordx4 v[114:115], v[110:113], off nt
	global_store_dwordx4 v[114:115], v[106:109], off offset:64 nt
	global_store_dwordx4 v[114:115], v[102:105], off offset:512 nt
	global_store_dwordx4 v[98:99], v[92:95], off nt
	global_store_dwordx4 v[98:99], v[88:91], off offset:64 nt
	global_store_dwordx4 v[98:99], v[84:87], off offset:512 nt
	global_store_dwordx4 v[80:81], v[76:79], off nt
	global_store_dwordx4 v[80:81], v[72:75], off offset:64 nt
	global_store_dwordx4 v[80:81], v[68:71], off offset:512 nt
	global_store_dwordx4 v[80:81], v[64:67], off offset:576 nt
	s_mov_b32 s24, 0x80000
	v_lshl_add_u64 v[92:93], s[66:67], 0, v[96:97]
	v_lshl_add_u64 v[64:65], s[68:69], 0, v[96:97]
	v_add_co_u32_e32 v66, vcc, s24, v64
	s_mov_b32 s68, 0xa0000
	s_nop 0
	v_addc_co_u32_e32 v67, vcc, 0, v65, vcc
	global_load_dwordx4 v[98:101], v[66:67], off
	global_load_dwordx4 v[102:105], v[66:67], off offset:64
	global_load_dwordx4 v[106:109], v[66:67], off offset:512
	global_load_dwordx4 v[110:113], v[66:67], off offset:576
	v_add_co_u32_e32 v66, vcc, s25, v64
	s_mov_b32 s69, 0xb0000
	s_nop 0
	v_addc_co_u32_e32 v67, vcc, 0, v65, vcc
	global_load_dwordx4 v[114:117], v[66:67], off
	global_load_dwordx4 v[118:121], v[66:67], off offset:64
	global_load_dwordx4 v[122:125], v[66:67], off offset:512
	global_load_dwordx4 v[126:129], v[66:67], off offset:576
	v_add_co_u32_e32 v66, vcc, s68, v64
	s_waitcnt vmcnt(7)
	v_pk_fma_f32 v[62:63], v[100:101], s[88:89], v[62:63] op_sel_hi:[1,0,1]
	v_addc_co_u32_e32 v67, vcc, 0, v65, vcc
	global_load_dwordx4 v[130:133], v[66:67], off
	global_load_dwordx4 v[88:91], v[66:67], off offset:64
	global_load_dwordx4 v[84:87], v[66:67], off offset:512
	global_load_dwordx4 v[80:83], v[66:67], off offset:576
	v_add_co_u32_e32 v64, vcc, s69, v64
	s_waitcnt vmcnt(8)
	v_pk_fma_f32 v[50:51], v[112:113], s[88:89], v[50:51] op_sel_hi:[1,0,1]
	v_addc_co_u32_e32 v65, vcc, 0, v65, vcc
	global_load_dwordx4 v[76:79], v[64:65], off
	global_load_dwordx4 v[72:75], v[64:65], off offset:64
	global_load_dwordx4 v[68:71], v[64:65], off offset:512
	s_nop 0
	global_load_dwordx4 v[64:67], v[64:65], off offset:576
	v_add_co_u32_e32 v94, vcc, s24, v92
	v_pk_fma_f32 v[48:49], v[110:111], s[88:89], v[48:49] op_sel_hi:[1,0,1]
	s_nop 0
	v_addc_co_u32_e32 v95, vcc, 0, v93, vcc
	global_store_dwordx4 v[94:95], v[48:51], off offset:576 nt
	s_waitcnt vmcnt(9)
	v_pk_fma_f32 v[30:31], v[128:129], s[88:89], v[30:31] op_sel_hi:[1,0,1]
	v_pk_fma_f32 v[28:29], v[126:127], s[88:89], v[28:29] op_sel_hi:[1,0,1]
	v_add_co_u32_e32 v48, vcc, s25, v92
	v_pk_fma_f32 v[60:61], v[98:99], s[88:89], v[60:61] op_sel_hi:[1,0,1]
	s_nop 0
	v_addc_co_u32_e32 v49, vcc, 0, v93, vcc
	global_store_dwordx4 v[48:49], v[28:31], off offset:576 nt
	v_pk_fma_f32 v[58:59], v[104:105], s[88:89], v[58:59] op_sel_hi:[1,0,1]
	v_pk_fma_f32 v[56:57], v[102:103], s[88:89], v[56:57] op_sel_hi:[1,0,1]
	v_pk_fma_f32 v[54:55], v[108:109], s[88:89], v[54:55] op_sel_hi:[1,0,1]
	v_pk_fma_f32 v[52:53], v[106:107], s[88:89], v[52:53] op_sel_hi:[1,0,1]
	v_pk_fma_f32 v[46:47], v[116:117], s[88:89], v[46:47] op_sel_hi:[1,0,1]
	v_pk_fma_f32 v[44:45], v[114:115], s[88:89], v[44:45] op_sel_hi:[1,0,1]
	v_pk_fma_f32 v[42:43], v[120:121], s[88:89], v[42:43] op_sel_hi:[1,0,1]
	v_pk_fma_f32 v[40:41], v[118:119], s[88:89], v[40:41] op_sel_hi:[1,0,1]
	v_pk_fma_f32 v[38:39], v[124:125], s[88:89], v[38:39] op_sel_hi:[1,0,1]
	v_pk_fma_f32 v[36:37], v[122:123], s[88:89], v[36:37] op_sel_hi:[1,0,1]
	global_store_dwordx4 v[94:95], v[60:63], off nt
	global_store_dwordx4 v[94:95], v[56:59], off offset:64 nt
	global_store_dwordx4 v[94:95], v[52:55], off offset:512 nt
	global_store_dwordx4 v[48:49], v[44:47], off nt
	global_store_dwordx4 v[48:49], v[40:43], off offset:64 nt
	global_store_dwordx4 v[48:49], v[36:39], off offset:512 nt
	s_waitcnt vmcnt(15)
	v_pk_fma_f32 v[28:29], v[130:131], s[88:89], v[32:33] op_sel_hi:[1,0,1]
	v_add_co_u32_e32 v32, vcc, s68, v92
	s_waitcnt vmcnt(12)
	v_pk_fma_f32 v[18:19], v[82:83], s[88:89], v[18:19] op_sel_hi:[1,0,1]
	v_addc_co_u32_e32 v33, vcc, 0, v93, vcc
	v_pk_fma_f32 v[16:17], v[80:81], s[88:89], v[16:17] op_sel_hi:[1,0,1]
	global_store_dwordx4 v[32:33], v[16:19], off offset:576 nt
	v_pk_fma_f32 v[30:31], v[132:133], s[88:89], v[34:35] op_sel_hi:[1,0,1]
	v_pk_fma_f32 v[26:27], v[90:91], s[88:89], v[26:27] op_sel_hi:[1,0,1]
	v_add_co_u32_e32 v16, vcc, s69, v92
	v_pk_fma_f32 v[24:25], v[88:89], s[88:89], v[24:25] op_sel_hi:[1,0,1]
	v_pk_fma_f32 v[22:23], v[86:87], s[88:89], v[22:23] op_sel_hi:[1,0,1]
	v_pk_fma_f32 v[20:21], v[84:85], s[88:89], v[20:21] op_sel_hi:[1,0,1]
	s_waitcnt vmcnt(12)
	v_pk_fma_f32 v[14:15], v[78:79], s[88:89], v[14:15] op_sel_hi:[1,0,1]
	v_pk_fma_f32 v[12:13], v[76:77], s[88:89], v[12:13] op_sel_hi:[1,0,1]
	v_addc_co_u32_e32 v17, vcc, 0, v93, vcc
	s_waitcnt vmcnt(11)
	v_pk_fma_f32 v[10:11], v[74:75], s[88:89], v[10:11] op_sel_hi:[1,0,1]
	v_pk_fma_f32 v[8:9], v[72:73], s[88:89], v[8:9] op_sel_hi:[1,0,1]
	s_waitcnt vmcnt(10)
	v_pk_fma_f32 v[6:7], v[70:71], s[88:89], v[6:7] op_sel_hi:[1,0,1]
	v_pk_fma_f32 v[4:5], v[68:69], s[88:89], v[4:5] op_sel_hi:[1,0,1]
	s_waitcnt vmcnt(9)
	v_pk_fma_f32 v[2:3], v[66:67], s[88:89], v[2:3] op_sel_hi:[1,0,1]
	v_pk_fma_f32 v[0:1], v[64:65], s[88:89], v[0:1] op_sel_hi:[1,0,1]
	global_store_dwordx4 v[32:33], v[28:31], off nt
	global_store_dwordx4 v[32:33], v[24:27], off offset:64 nt
	global_store_dwordx4 v[32:33], v[20:23], off offset:512 nt
	global_store_dwordx4 v[16:17], v[12:15], off nt
	global_store_dwordx4 v[16:17], v[8:11], off offset:64 nt
	global_store_dwordx4 v[16:17], v[4:7], off offset:512 nt
	global_store_dwordx4 v[16:17], v[0:3], off offset:576 nt
